# f1g/f1u weight transposes moved from PREP into the ADA phase's 112 transposer workgroups, all using the hand-written LDS-free transposer
# speedup vs baseline: 1.0281x; 1.0106x over previous
.LBB0_85:
	s_or_b64 exec, exec, s[6:7]
.LBB0_154:
.LBB0_155:
	s_cmp_lt_i32 s92, 2
	s_cselect_b64 s[0:1], -1, 0
	s_cmp_gt_i32 s93, 1
	s_cselect_b64 s[4:5], -1, 0
	s_and_b64 s[4:5], s[0:1], s[4:5]
	s_andn2_b64 vcc, exec, s[4:5]
	s_cbranch_vccnz .LBB0_269
	s_andn2_b64 vcc, exec, s[2:3]
	s_cbranch_vccnz .LBB0_210
	s_waitcnt vmcnt(0)
	s_barrier
	s_mov_b64 s[2:3], exec
	v_readlane_b32 s4, v235, 17
	v_readlane_b32 s5, v235, 18
	s_and_b64 s[4:5], s[2:3], s[4:5]
	s_mov_b64 exec, s[4:5]
	s_cbranch_execz .LBB0_209
	s_add_i32 s4, 0, 0x23ff0
	v_mov_b32_e32 v0, s4
	s_waitcnt vmcnt(0) expcnt(0) lgkmcnt(0)
	ds_read_b32 v2, v0
	s_add_i32 s4, 0, 0x23ff4
	v_mov_b32_e32 v0, s4
	ds_read_b32 v0, v0
	s_waitcnt lgkmcnt(1)
	v_cmp_ne_u32_e32 vcc, 0, v2
	s_cbranch_vccnz .LBB0_173
	v_readlane_b32 s4, v235, 0
	s_mul_i32 s28, s95, s4
	s_add_u32 s4, s50, 0x1000
	s_addc_u32 s5, s51, 0
	s_add_u32 s6, s50, 0x1100
	s_addc_u32 s7, s51, 0
	s_add_u32 s8, s50, 0x1200
	s_addc_u32 s9, s51, 0
	s_add_u32 s10, s50, 0x1300
	s_mul_i32 s28, s28, s94
	s_addc_u32 s11, s51, 0
	s_mov_b32 s29, 1
	v_mov_b32_e32 v16, 0
	s_branch .LBB0_161

.LBB0_260:
	s_and_b64 vcc, exec, s[2:3]
	s_cbranch_vccz .LBB0_269
	s_sub_u32 s87, s34, 0x90
	v_readfirstlane_b32 s88, v128
	s_lshr_b32 s88, s88, 6
	s_lshl_b32 s87, s87, 3
	s_add_u32 s65, s87, s88
	s_sub_u32 s66, s94, 0x90
	s_lshl_b32 s66, s66, 3
	s_mov_b32 s64, 0
	s_mov_b32 s68, 0x1600
	s_mov_b32 s67, 0
	s_branch .LT_entry

.LT_ret1:
	s_sub_u32 s65, s65, s68
	s_mov_b32 s64, 3
	s_mov_b32 s68, 0x2280
	s_mov_b32 s67, 2
	s_branch .LT_entry
.LT_ret2:
	s_sub_u32 s65, s65, s68
.LBB0_269:
	s_cmp_lt_i32 s92, 3
	s_cselect_b64 s[6:7], -1, 0
	s_cmp_gt_i32 s93, 2
	s_cselect_b64 s[2:3], -1, 0
	s_and_b64 s[2:3], s[6:7], s[2:3]
	s_andn2_b64 vcc, exec, s[2:3]
	s_cbranch_vccnz .LBB0_330
	s_andn2_b64 vcc, exec, s[0:1]
	s_cbranch_vccnz .LBB0_324
	s_waitcnt vmcnt(0)
	s_barrier
	s_mov_b64 s[0:1], exec
	v_readlane_b32 s2, v235, 17
	v_readlane_b32 s3, v235, 18
	s_and_b64 s[2:3], s[0:1], s[2:3]
	s_mov_b64 exec, s[2:3]
	s_cbranch_execz .LBB0_323
	s_add_i32 s2, 0, 0x23ff0
	v_mov_b32_e32 v0, s2
	s_waitcnt vmcnt(0) expcnt(0) lgkmcnt(0)
	ds_read_b32 v2, v0
	s_add_i32 s2, 0, 0x23ff4
	v_mov_b32_e32 v0, s2
	ds_read_b32 v0, v0
	s_waitcnt lgkmcnt(1)
	v_cmp_ne_u32_e32 vcc, 0, v2
	s_cbranch_vccnz .LBB0_287
	v_readlane_b32 s2, v235, 0
	s_mul_i32 s28, s95, s2
	s_add_u32 s2, s50, 0x1000
	s_addc_u32 s3, s51, 0
	s_add_u32 s4, s50, 0x1100
	s_addc_u32 s5, s51, 0
	s_add_u32 s8, s50, 0x1200
	s_addc_u32 s9, s51, 0
	s_add_u32 s10, s50, 0x1300
	s_mul_i32 s28, s28, s94
	s_addc_u32 s11, s51, 0
	s_mov_b32 s29, 1
	v_mov_b32_e32 v16, 0
	s_branch .LBB0_275

.LT_done:
	s_cmp_eq_u32 s67, 0
	s_cbranch_scc1 .LT_ret0
	s_cmp_eq_u32 s67, 1
	s_cbranch_scc1 .LT_ret1
	s_cmp_eq_u32 s67, 2
	s_cbranch_scc1 .LT_ret2
	s_endpgm
